# MLA tile loop: next-tile K/V global loads and pointer steps moved from the tile head to behind the first block's LDS reads (absolute pointers, plain global loads)
# speedup vs baseline: 1.0132x; 1.0074x over previous
; DI float xhalf_sum(float m) { auto rr = __builtin_amdgcn_permlane32_swap(__float_as_uint(m), __float_as_uint(m), false, false); return __uint_as_float(rr[0]) + __uint_as_float(rr[1]); }
; template <int DQK, int DV, bool CAUSAL, int KT, bool PRIO>
; DI void attn_unit(const bf16_t* Qb, int qpitch, const bf16_t* Kb, int kpitch, const bf16_t* Vtb, int vpitch, bf16_t* Ob, int opitch, int q0, int nt, LAS unsigned char* lds, float kbound, const float* qgain, const int* qpos, float qscale) {
;     ...
;     if (PRIO) {
;         float q2 = 0.f;
; #pragma unroll
;         for (int ks = 0; ks < DQK / 16; ++ks)
; #pragma unroll
;             for (int e = 0; e < 8; ++e) { const float v = __uint_as_float(((unsigned)(unsigned short)qf[ks][e]) << 16); q2 += v * v; }
;         q2 = xhalf_sum(q2);
;         nomax = __all(sqrtf(q2) * kbound <= 100.0f) != 0;
.LBB0_1486:
	s_waitcnt vmcnt(0) lgkmcnt(0)
	v_and_b32_e32 v9, 0xffff0000, v116
	v_lshlrev_b32_e32 v8, 16, v116
	v_mul_f32_e32 v11, v9, v9
	v_fmac_f32_e32 v11, v8, v8
	v_lshlrev_b32_e32 v8, 16, v117
	v_fmac_f32_e32 v11, v8, v8
	v_and_b32_e32 v8, 0xffff0000, v117
	v_fmac_f32_e32 v11, v8, v8
	v_lshlrev_b32_e32 v8, 16, v118
	v_fmac_f32_e32 v11, v8, v8
	v_and_b32_e32 v8, 0xffff0000, v118
	v_fmac_f32_e32 v11, v8, v8
	v_lshlrev_b32_e32 v8, 16, v119
	v_fmac_f32_e32 v11, v8, v8
	v_and_b32_e32 v8, 0xffff0000, v119
	v_fmac_f32_e32 v11, v8, v8
	v_lshlrev_b32_e32 v8, 16, v120
	v_fmac_f32_e32 v11, v8, v8
	v_and_b32_e32 v8, 0xffff0000, v120
	v_fmac_f32_e32 v11, v8, v8
	v_lshlrev_b32_e32 v8, 16, v121
	v_fmac_f32_e32 v11, v8, v8
	v_and_b32_e32 v8, 0xffff0000, v121
	v_fmac_f32_e32 v11, v8, v8
	v_lshlrev_b32_e32 v8, 16, v122
	v_fmac_f32_e32 v11, v8, v8
	v_and_b32_e32 v8, 0xffff0000, v122
	v_fmac_f32_e32 v11, v8, v8
	v_lshlrev_b32_e32 v8, 16, v123
	v_fmac_f32_e32 v11, v8, v8
	v_and_b32_e32 v8, 0xffff0000, v123
	v_fmac_f32_e32 v11, v8, v8
	v_lshlrev_b32_e32 v8, 16, v124
	v_fmac_f32_e32 v11, v8, v8
	v_and_b32_e32 v8, 0xffff0000, v124
	v_fmac_f32_e32 v11, v8, v8
	v_lshlrev_b32_e32 v8, 16, v125
	v_fmac_f32_e32 v11, v8, v8
	v_and_b32_e32 v8, 0xffff0000, v125
	v_fmac_f32_e32 v11, v8, v8
	v_lshlrev_b32_e32 v8, 16, v126
	v_fmac_f32_e32 v11, v8, v8
	v_and_b32_e32 v8, 0xffff0000, v126
	v_fmac_f32_e32 v11, v8, v8
	v_lshlrev_b32_e32 v8, 16, v127
	v_fmac_f32_e32 v11, v8, v8
	v_and_b32_e32 v8, 0xffff0000, v127
	v_fmac_f32_e32 v11, v8, v8
	v_lshlrev_b32_e32 v8, 16, v128
	v_fmac_f32_e32 v11, v8, v8
	v_and_b32_e32 v8, 0xffff0000, v128
	v_fmac_f32_e32 v11, v8, v8
	v_lshlrev_b32_e32 v8, 16, v129
	v_fmac_f32_e32 v11, v8, v8
	v_and_b32_e32 v8, 0xffff0000, v129
	v_fmac_f32_e32 v11, v8, v8
	v_lshlrev_b32_e32 v8, 16, v130
	v_fmac_f32_e32 v11, v8, v8
	v_and_b32_e32 v8, 0xffff0000, v130
	v_fmac_f32_e32 v11, v8, v8
	v_lshlrev_b32_e32 v8, 16, v131
	v_fmac_f32_e32 v11, v8, v8
	v_and_b32_e32 v8, 0xffff0000, v131
	v_fmac_f32_e32 v11, v8, v8
	v_lshlrev_b32_e32 v8, 16, v132
	v_fmac_f32_e32 v11, v8, v8
	v_and_b32_e32 v8, 0xffff0000, v132
	v_fmac_f32_e32 v11, v8, v8
	v_lshlrev_b32_e32 v8, 16, v133
	v_fmac_f32_e32 v11, v8, v8
	v_and_b32_e32 v8, 0xffff0000, v133
	v_fmac_f32_e32 v11, v8, v8
	v_lshlrev_b32_e32 v8, 16, v134
	v_fmac_f32_e32 v11, v8, v8
	v_and_b32_e32 v8, 0xffff0000, v134
	v_fmac_f32_e32 v11, v8, v8
	v_lshlrev_b32_e32 v8, 16, v135
	v_fmac_f32_e32 v11, v8, v8
	v_and_b32_e32 v8, 0xffff0000, v135
	v_fmac_f32_e32 v11, v8, v8
	v_lshlrev_b32_e32 v8, 16, v136
	v_fmac_f32_e32 v11, v8, v8
	v_and_b32_e32 v8, 0xffff0000, v136
	v_fmac_f32_e32 v11, v8, v8
	v_and_b32_e32 v9, 0xffff0000, v137
	v_lshlrev_b32_e32 v8, 16, v137
	v_pk_mul_f32 v[8:9], v[8:9], v[8:9]
	s_xor_b64 s[34:35], s[2:3], -1
	v_add_f32_e32 v8, v8, v11
	v_add_f32_e32 v11, v9, v8
	v_and_b32_e32 v9, 0xffff0000, v138
	v_lshlrev_b32_e32 v8, 16, v138
	v_pk_mul_f32 v[8:9], v[8:9], v[8:9]
	v_mad_i64_i32 v[2:3], s[2:3], v149, s88, 0
	v_add_f32_e32 v8, v8, v11
	v_add_f32_e32 v11, v9, v8
	v_and_b32_e32 v9, 0xffff0000, v139
	v_lshlrev_b32_e32 v8, 16, v139
	v_pk_mul_f32 v[8:9], v[8:9], v[8:9]
	v_mad_i64_i32 v[4:5], s[2:3], v151, s88, 0
	v_add_f32_e32 v8, v8, v11
	v_add_f32_e32 v8, v9, v8
	v_mov_b32_e32 v9, v8
	s_nop 1
	v_permlane32_swap_b32_e32 v8, v9
	v_add_f32_e32 v8, v8, v9
	v_mul_f32_e32 v9, 0x4f800000, v8
	v_cmp_gt_f32_e32 vcc, s91, v8
	v_mad_i64_i32 v[6:7], s[2:3], v153, s88, 0
	s_nop 0
	v_cndmask_b32_e32 v8, v8, v9, vcc
	v_sqrt_f32_e32 v9, v8
	s_add_i32 s2, s38, 0x100
	s_lshr_b32 s68, s2, 7
	v_mul_lo_u32 v178, v149, s53
	v_add_u32_e32 v11, -1, v9
	v_fma_f32 v12, -v11, v9, v8
; #define LAS __attribute__((address_space(3)))
; DI float xhalf_sum(float m) { auto rr = __builtin_amdgcn_permlane32_swap(__float_as_uint(m), __float_as_uint(m), false, false); return __uint_as_float(rr[0]) + __uint_as_float(rr[1]); }
; template <int DQK, int DV, bool CAUSAL, int KT, bool PRIO>
; DI void attn_unit(const bf16_t* Qb, int qpitch, const bf16_t* Kb, int kpitch, const bf16_t* Vtb, int vpitch, bf16_t* Ob, int opitch, int q0, int nt, LAS unsigned char* lds, float kbound, const float* qgain, const int* qpos, float qscale) {
;     ...
;     auto gload = [&](int kt) {
; #pragma unroll
;         for (int i = 0; i < NKR; ++i) { const int c = tid + i * 512; if (NKC % 512 == 0 || c < NKC) kreg[i] = *(const u32x4*)(Kb + (size_t)(kt * KT + c / KCH) * kpitch + (c % KCH) * 8); }
; #pragma unroll
;         for (int i = 0; i < NVR; ++i) { const int c = tid + i * 512; vreg[i] = *(const u32x4*)(Vtb + (size_t)(c / VCH) * vpitch + kt * KT + (c % VCH) * 8); }
;     };
;     auto lstore = [&](int buf) {
; #pragma unroll
;         for (int i = 0; i < NKR; ++i) { const int c = tid + i * 512; if (NKC % 512 == 0 || c < NKC) *(LAS u32x4*)(lds + buf * KBUF + (c / KCH) * KS + (c % KCH) * 16) = kreg[i]; }
; #pragma unroll
;         for (int i = 0; i < NVR; ++i) { const int c = tid + i * 512; LAS unsigned char* p = lds + VOFF + buf * VBUF + (c / VCH) * VS + (c % VCH) * 16;
;             *(LAS u32x2*)p = (u32x2){vreg[i].x, vreg[i].y}; *(LAS u32x2*)(p + 8) = (u32x2){vreg[i].z, vreg[i].w}; }
;     };
;     ...
;     f32x16 o[DV / 32], negm;
; #pragma unroll
;     for (int i = 0; i < 16; ++i) negm[i] = 0.f;
; #pragma unroll
;     for (int d = 0; d < DV / 32; ++d)
; #pragma unroll
;         for (int i = 0; i < 16; ++i) o[d][i] = 0.f;
;     float mrun = 0.f, lrun = 0.f; bool first = true;
;     bool nomax = false;
;     if (PRIO) {
;         float q2 = 0.f;
; #pragma unroll
;         for (int ks = 0; ks < DQK / 16; ++ks)
; #pragma unroll
;             for (int e = 0; e < 8; ++e) { const float v = __uint_as_float(((unsigned)(unsigned short)qf[ks][e]) << 16); q2 += v * v; }
;         q2 = xhalf_sum(q2);
;         nomax = __all(sqrtf(q2) * kbound <= 100.0f) != 0;
;     }
;     lstore(0);
;     __syncthreads();
;     const int qabs = q0 + 32 * w + r, qlo = q0 + 32 * w;
	v_cmp_ge_f32_e64 s[2:3], 0, v12
	v_add_u32_e32 v12, 1, v9
	v_lshlrev_b32_e32 v179, 4, v150
	v_cndmask_b32_e64 v11, v9, v11, s[2:3]
	v_fma_f32 v9, -v12, v9, v8
	v_cmp_lt_f32_e64 s[2:3], 0, v9
	v_mul_lo_u32 v181, v151, s53
	v_lshlrev_b32_e32 v182, 4, v152
	v_cndmask_b32_e64 v9, v11, v12, s[2:3]
	v_mul_f32_e32 v11, 0x37800000, v9
	v_cndmask_b32_e32 v9, v9, v11, vcc
	v_cmp_class_f32_e32 vcc, v8, v176
	v_mul_lo_u32 v183, v153, s53
	v_lshlrev_b32_e32 v184, 4, v154
	v_cndmask_b32_e32 v8, v9, v8, vcc
	v_mul_f32_e32 v8, v174, v8
	v_cmp_ge_f32_e32 vcc, s52, v8
	v_add3_u32 v8, 0, v178, v179
	ds_write_b128 v8, v[96:99]
	v_add3_u32 v8, 0, v181, v182
	ds_write_b128 v8, v[100:103]
	v_add3_u32 v8, 0, v183, v184
	v_mul_lo_u32 v185, v68, s56
	ds_write_b128 v8, v[104:107]
	v_add_u32_e32 v8, 0, v185
	v_and_b32_e32 v186, 1, v69
	v_lshlrev_b32_e32 v186, 3, v186
	v_sub_u32_e32 v186, 0, v186
	v_lshl_add_u32 v186, v69, 4, v186
	v_add3_u32 v8, v8, v186, s57
	v_mul_lo_u32 v187, v74, s56
	ds_write2_b64 v8, v[108:109], v[110:111] offset1:2
	v_add_u32_e32 v8, 0, v187
	v_and_b32_e32 v188, 1, v75
	v_lshlrev_b32_e32 v188, 3, v188
	v_sub_u32_e32 v188, 0, v188
	v_lshl_add_u32 v188, v75, 4, v188
	v_and_b32_e32 v10, 31, v155
	v_add3_u32 v8, v8, v188, s57
	s_ashr_i32 s27, s26, 31
	s_and_b32 s69, s39, 0xffffffe0
	ds_write2_b64 v8, v[112:113], v[114:115] offset1:2
	v_mul_u32_u24_e32 v8, 0x110, v10
	s_cmp_lg_u64 vcc, exec
	v_add3_u32 v191, v0, v8, v0
	v_lshl_add_u64 v[8:9], s[22:23], 0, v[70:71]
	s_cselect_b64 s[2:3], -1, 0
	s_add_i32 s69, s69, s38
	v_lshl_add_u64 v[164:165], v[72:73], 1, v[8:9]
	v_lshl_add_u64 v[8:9], s[22:23], 0, v[64:65]
	v_lshl_add_u64 v[6:7], s[24:25], 0, v[6:7]
	v_lshl_add_u64 v[4:5], s[24:25], 0, v[4:5]
	v_lshl_add_u64 v[2:3], s[24:25], 0, v[2:3]
	v_mov_b32_e32 v14, v1
	v_mov_b32_e32 v15, v1
	v_or_b32_e32 v189, s69, v10
	v_mul_u32_u24_e32 v192, 0xd0, v10
	v_lshl_add_u64 v[166:167], v[66:67], 1, v[8:9]
	v_lshl_add_u64 v[168:169], v[62:63], 1, v[6:7]
	v_lshl_add_u64 v[170:171], v[60:61], 1, v[4:5]
	v_lshl_add_u64 v[172:173], v[58:59], 1, v[2:3]
	v_lshl_add_u64 v[164:165], s[4:5], 0, v[164:165]
	v_lshl_add_u64 v[166:167], s[4:5], 0, v[166:167]
	v_lshl_add_u64 v[168:169], s[4:5], 0, v[168:169]
	v_lshl_add_u64 v[170:171], s[4:5], 0, v[170:171]
	v_lshl_add_u64 v[172:173], s[4:5], 0, v[172:173]
	s_nop 0
	s_nop 0
	s_nop 0
	s_nop 0
	s_nop 0
	s_nop 0
	v_mov_b32_e32 v0, v1
	v_mov_b32_e32 v2, v1
	v_mov_b32_e32 v3, v1
	v_mov_b32_e32 v4, v1
	v_mov_b32_e32 v5, v1
	v_mov_b32_e32 v6, v1
	v_mov_b32_e32 v7, v1
	v_mov_b32_e32 v8, v1
	v_mov_b32_e32 v9, v1
	v_mov_b32_e32 v10, v1
	v_mov_b32_e32 v11, v1
	v_mov_b32_e32 v12, v1
	v_mov_b32_e32 v13, v1
	v_mov_b64_e32 v[30:31], v[14:15]
	v_mov_b64_e32 v[46:47], v[14:15]
	v_mov_b64_e32 v[62:63], v[14:15]
	s_mov_b32 s12, 0
	s_or_b32 s70, s69, 31
	v_lshl_add_u32 v190, v148, 4, 0
	v_lshlrev_b32_e32 v180, 2, v148
	s_mov_b64 s[40:41], -1
	v_mov_b32_e32 v193, 0
	s_mov_b32 s71, 63
	v_mov_b64_e32 v[28:29], v[12:13]
	v_mov_b64_e32 v[26:27], v[10:11]
	v_mov_b64_e32 v[24:25], v[8:9]
	v_mov_b64_e32 v[22:23], v[6:7]
	v_mov_b64_e32 v[20:21], v[4:5]
	v_mov_b64_e32 v[18:19], v[2:3]
	v_mov_b64_e32 v[16:17], v[0:1]
	v_mov_b64_e32 v[44:45], v[12:13]
	v_mov_b64_e32 v[42:43], v[10:11]
	v_mov_b64_e32 v[40:41], v[8:9]
	v_mov_b64_e32 v[38:39], v[6:7]
	v_mov_b64_e32 v[36:37], v[4:5]
	v_mov_b64_e32 v[34:35], v[2:3]
	v_mov_b64_e32 v[32:33], v[0:1]
	v_mov_b64_e32 v[60:61], v[12:13]
	v_mov_b64_e32 v[58:59], v[10:11]
	v_mov_b64_e32 v[56:57], v[8:9]
	v_mov_b64_e32 v[54:55], v[6:7]
	v_mov_b64_e32 v[52:53], v[4:5]
	v_mov_b64_e32 v[50:51], v[2:3]
	v_mov_b64_e32 v[48:49], v[0:1]
	v_mov_b32_e32 v0, 0
	s_waitcnt lgkmcnt(0)
	s_barrier

; template <int DQK, int DV, bool CAUSAL, int KT, bool PRIO>
; DI void attn_unit(const bf16_t* Qb, int qpitch, const bf16_t* Kb, int kpitch, const bf16_t* Vtb, int vpitch, bf16_t* Ob, int opitch, int q0, int nt, LAS unsigned char* lds, float kbound, const float* qgain, const int* qpos, float qscale) {
;     ...
;     auto gload = [&](int kt) {
; #pragma unroll
;         for (int i = 0; i < NKR; ++i) { const int c = tid + i * 512; if (NKC % 512 == 0 || c < NKC) kreg[i] = *(const u32x4*)(Kb + (size_t)(kt * KT + c / KCH) * kpitch + (c % KCH) * 8); }
; #pragma unroll
;         for (int i = 0; i < NVR; ++i) { const int c = tid + i * 512; vreg[i] = *(const u32x4*)(Vtb + (size_t)(c / VCH) * vpitch + kt * KT + (c % VCH) * 8); }
;     };
;     ...
;     for (int kt = 0; kt < nt; ++kt) {
;         const int buf = kt & 1;
;         if (kt + 1 < nt) gload(kt + 1);
; #pragma unroll
;         for (int hf = 0; hf < KT / 64; ++hf) {
;             const int key0 = kt * KT + 64 * hf;
;             if (!CAUSAL || key0 <= qlo + 31) {
.LBB0_1489:
	s_and_b32 s75, s12, 1
	s_mul_i32 s13, s75, 0x6800
	v_add_u32_e32 v2, s13, v190
	s_mul_i32 s13, s75, 0x4400
	s_sub_i32 s12, s71, 63
	v_add_u32_e32 v194, v2, v192
	v_add_u32_e32 v2, s13, v191
	s_cmp_gt_i32 s12, s70
	v_add_u32_e32 v14, 0xd000, v2
	v_add_u32_e32 v15, 0xf200, v2
	s_cbranch_scc0 .LBB0_1495
	global_load_dwordx4 v[96:99], v[172:173], off
	global_load_dwordx4 v[100:103], v[170:171], off
	global_load_dwordx4 v[104:107], v[168:169], off
	global_load_dwordx4 v[108:111], v[166:167], off
	global_load_dwordx4 v[112:115], v[164:165], off
	v_lshl_add_u64 v[164:165], v[164:165], 0, s[14:15]
	v_lshl_add_u64 v[166:167], v[166:167], 0, s[14:15]
	v_lshl_add_u64 v[168:169], v[168:169], 0, s[16:17]
	v_lshl_add_u64 v[170:171], v[170:171], 0, s[16:17]
	v_lshl_add_u64 v[172:173], v[172:173], 0, s[16:17]
	s_add_i32 s12, s71, 1
	s_cmp_gt_i32 s12, s70
	s_cbranch_scc0 .Lmla_b1_pre

; template <int DQK, int DV, bool CAUSAL, int KT, bool PRIO>
; DI void attn_unit(const bf16_t* Qb, int qpitch, const bf16_t* Kb, int kpitch, const bf16_t* Vtb, int vpitch, bf16_t* Ob, int opitch, int q0, int nt, LAS unsigned char* lds, float kbound, const float* qgain, const int* qpos, float qscale) {
;     ...
;         if (kt + 1 < nt) lstore(buf ^ 1);
;         __syncthreads();
;     }
.LBB0_1493:
	s_addk_i32 s71, 0x80
	s_cmp_lg_u32 s68, s74
	s_waitcnt lgkmcnt(0)
	s_barrier
	s_cbranch_scc0 .LBB0_1479
	s_mov_b32 s12, s74
	s_branch .LBB0_1487

; template <int DQK, int DV, bool CAUSAL, int KT, bool PRIO>
; DI void attn_unit(const bf16_t* Qb, int qpitch, const bf16_t* Kb, int kpitch, const bf16_t* Vtb, int vpitch, bf16_t* Ob, int opitch, int q0, int nt, LAS unsigned char* lds, float kbound, const float* qgain, const int* qpos, float qscale) {
;     ...
;     auto gload = [&](int kt) {
; #pragma unroll
;         for (int i = 0; i < NKR; ++i) { const int c = tid + i * 512; if (NKC % 512 == 0 || c < NKC) kreg[i] = *(const u32x4*)(Kb + (size_t)(kt * KT + c / KCH) * kpitch + (c % KCH) * 8); }
; #pragma unroll
;         for (int i = 0; i < NVR; ++i) { const int c = tid + i * 512; vreg[i] = *(const u32x4*)(Vtb + (size_t)(c / VCH) * vpitch + kt * KT + (c % VCH) * 8); }
;     ...
;             if (!CAUSAL || key0 <= qlo + 31) {
;                 if (PRIO) {
;                     constexpr int KSN = DQK / 16, NDB = DV / 32;
;                     f32x16 s0 = negm, s1 = negm;
;                     const LAS unsigned char* kb = lds + buf * KBUF + (64 * hf + r) * KS + h * 16;
;                     const LAS unsigned char* vb = lds + VOFF + buf * VBUF + r * VS + h * 8 + 128 * hf;
;                     bf16x8 kf0[KSN], kf1[KSN], vf[4][NDB];
; #pragma unroll
;                     for (int ks = 0; ks < KSN; ++ks) { kf0[ks] = *(const LAS bf16x8*)(kb + ks * 32); kf1[ks] = *(const LAS bf16x8*)(kb + 32 * KS + ks * 32); }
;                     __builtin_amdgcn_sched_barrier(0); __builtin_amdgcn_s_setprio(1); __builtin_amdgcn_sched_barrier(0);
; #pragma unroll
;                     for (int ks = 0; ks < KSN; ++ks) { s0 = MFMA32(kf0[ks], qf[ks], s0); s1 = MFMA32(kf1[ks], qf[ks], s1); }
;                     __builtin_amdgcn_sched_barrier(0); __builtin_amdgcn_s_setprio(0); __builtin_amdgcn_sched_barrier(0);
; #pragma unroll
;                     for (int q4 = 0; q4 < 4; ++q4)
; #pragma unroll
;                         for (int d = 0; d < NDB; ++d) { const LAS unsigned char* vp = vb + d * 32 * VS + q4 * 32;
;                             const s16x4 lo = *(const LAS s16x4*)vp, hi = *(const LAS s16x4*)(vp + 16); vf[q4][d] = (bf16x8){lo[0], lo[1], lo[2], lo[3], hi[0], hi[1], hi[2], hi[3]}; }
;                     if (CAUSAL && key0 + 63 > qlo) {
; #pragma unroll
;                         for (int i = 0; i < 16; ++i) { const int key = key0 + (i & 3) + 8 * (i >> 2) + 4 * h; if (key > qabs) s0[i] = -1e30f; if (key + 32 > qabs) s1[i] = -1e30f; }
.LBB0_1495:
	ds_read_b128 v[2:5], v194
	ds_read_b128 v[6:9], v194 offset:32
	ds_read_b128 v[10:13], v194 offset:6656
	ds_read_b128 v[140:143], v194 offset:6688
	ds_read_b128 v[144:147], v194 offset:64
	ds_read_b128 v[148:151], v194 offset:96
	ds_read_b128 v[152:155], v194 offset:6720
	ds_read_b128 v[156:159], v194 offset:6752
	ds_read_b128 v[198:201], v194 offset:128
	ds_read_b128 v[202:205], v194 offset:160
	ds_read_b128 v[206:209], v194 offset:6784
	ds_read_b128 v[210:213], v194 offset:6816
	global_load_dwordx4 v[96:99], v[172:173], off
	global_load_dwordx4 v[100:103], v[170:171], off
	global_load_dwordx4 v[104:107], v[168:169], off
	global_load_dwordx4 v[108:111], v[166:167], off
	global_load_dwordx4 v[112:115], v[164:165], off
	v_lshl_add_u64 v[164:165], v[164:165], 0, s[14:15]
	v_lshl_add_u64 v[166:167], v[166:167], 0, s[14:15]
	v_lshl_add_u64 v[168:169], v[168:169], 0, s[16:17]
	v_lshl_add_u64 v[170:171], v[170:171], 0, s[16:17]
	v_lshl_add_u64 v[172:173], v[172:173], 0, s[16:17]
	s_setprio 1
	s_setprio 0
	s_waitcnt lgkmcnt(0)
	v_mfma_f32_32x32x16_bf16 v[80:95], v[2:5], v[116:119], v[48:63]
	s_cmp_le_i32 s71, s69
	v_mfma_f32_32x32x16_bf16 v[64:79], v[10:13], v[116:119], v[48:63]
	v_mfma_f32_32x32x16_bf16 v[80:95], v[6:9], v[120:123], v[80:95]
	v_mfma_f32_32x32x16_bf16 v[64:79], v[140:143], v[120:123], v[64:79]
	v_mfma_f32_32x32x16_bf16 v[80:95], v[144:147], v[124:127], v[80:95]
	v_mfma_f32_32x32x16_bf16 v[64:79], v[152:155], v[124:127], v[64:79]
	ds_read_b128 v[152:155], v14
	ds_read_b128 v[140:143], v14 offset:32
	v_mfma_f32_32x32x16_bf16 v[80:95], v[148:151], v[128:131], v[80:95]
	v_mfma_f32_32x32x16_bf16 v[64:79], v[156:159], v[128:131], v[64:79]
	ds_read_b128 v[156:159], v15
	ds_read_b128 v[148:151], v15 offset:32
	ds_read_b128 v[144:147], v14 offset:64
	ds_read_b128 v[10:13], v15 offset:64
	ds_read_b128 v[6:9], v14 offset:96
	ds_read_b128 v[2:5], v15 offset:96
	v_mfma_f32_32x32x16_bf16 v[80:95], v[198:201], v[132:135], v[80:95]
	v_mfma_f32_32x32x16_bf16 v[64:79], v[206:209], v[132:135], v[64:79]
	v_mfma_f32_32x32x16_bf16 v[80:95], v[202:205], v[136:139], v[80:95]
	v_mfma_f32_32x32x16_bf16 v[64:79], v[210:213], v[136:139], v[64:79]
	ds_read_b128 v[214:217], v194 offset:13312
	ds_read_b128 v[218:221], v194 offset:13344
	ds_read_b128 v[222:225], v194 offset:19968
	ds_read_b128 v[226:229], v194 offset:20000
	ds_read_b128 v[230:233], v194 offset:13376
	ds_read_b128 v[234:237], v194 offset:13408
	ds_read_b128 v[238:241], v194 offset:20032
	ds_read_b128 v[242:245], v194 offset:20064
	s_cbranch_scc1 .LBB0_1497
	v_add_u32_e32 v195, s71, v180
	v_subrev_u32_e32 v198, 31, v195
	v_subrev_u32_e32 v197, 63, v195
	v_cmp_le_i32_e32 vcc, v198, v189
	s_nop 6
	v_cndmask_b32_e32 v64, v177, v64, vcc
	v_cmp_lt_i32_e32 vcc, v197, v189
	s_nop 1
	v_cndmask_b32_e32 v81, v177, v81, vcc
	v_cmp_le_i32_e32 vcc, v197, v189
	v_subrev_u32_e32 v197, 30, v195
	s_nop 0
	v_cndmask_b32_e32 v80, v177, v80, vcc
	v_cmp_le_i32_e32 vcc, v197, v189
	v_subrev_u32_e32 v197, 61, v195
	s_nop 0
	v_cndmask_b32_e32 v65, v177, v65, vcc
	v_cmp_le_i32_e32 vcc, v197, v189
	v_subrev_u32_e32 v197, 29, v195
	s_nop 0
	v_cndmask_b32_e32 v82, v177, v82, vcc
	v_cmp_le_i32_e32 vcc, v197, v189
	v_subrev_u32_e32 v197, 60, v195
	s_nop 0
	v_cndmask_b32_e32 v66, v177, v66, vcc
	v_cmp_le_i32_e32 vcc, v197, v189
	v_subrev_u32_e32 v197, 28, v195
	s_nop 0
	v_cndmask_b32_e32 v83, v177, v83, vcc
	v_cmp_le_i32_e32 vcc, v197, v189
	v_subrev_u32_e32 v197, 55, v195
	s_nop 0
	v_cndmask_b32_e32 v67, v177, v67, vcc
	v_cmp_le_i32_e32 vcc, v197, v189
	v_subrev_u32_e32 v197, 23, v195
	s_nop 0
	v_cndmask_b32_e32 v84, v177, v84, vcc
	v_cmp_le_i32_e32 vcc, v197, v189
	v_subrev_u32_e32 v197, 54, v195
	s_nop 0
	v_cndmask_b32_e32 v68, v177, v68, vcc
	v_cmp_le_i32_e32 vcc, v197, v189
	v_subrev_u32_e32 v197, 22, v195
	s_nop 0
	v_cndmask_b32_e32 v85, v177, v85, vcc
	v_cmp_le_i32_e32 vcc, v197, v189
	v_subrev_u32_e32 v197, 53, v195
	s_nop 0
	v_cndmask_b32_e32 v69, v177, v69, vcc
	v_cmp_le_i32_e32 vcc, v197, v189
	v_subrev_u32_e32 v197, 21, v195
	s_nop 0
	v_cndmask_b32_e32 v86, v177, v86, vcc
	v_cmp_le_i32_e32 vcc, v197, v189
	v_subrev_u32_e32 v197, 52, v195
	s_nop 0
	v_cndmask_b32_e32 v70, v177, v70, vcc
	v_cmp_le_i32_e32 vcc, v197, v189
	v_subrev_u32_e32 v197, 20, v195
	s_nop 0
	v_cndmask_b32_e32 v87, v177, v87, vcc
	v_cmp_le_i32_e32 vcc, v197, v189
	v_subrev_u32_e32 v197, 47, v195
	s_nop 0
	v_cndmask_b32_e32 v71, v177, v71, vcc
	v_cmp_le_i32_e32 vcc, v197, v189
	v_add_u32_e32 v197, -15, v195
	s_nop 0
	v_cndmask_b32_e32 v88, v177, v88, vcc
	v_cmp_le_i32_e32 vcc, v197, v189
	v_subrev_u32_e32 v197, 46, v195
	s_nop 0
	v_cndmask_b32_e32 v72, v177, v72, vcc
	v_cmp_le_i32_e32 vcc, v197, v189
	v_add_u32_e32 v197, -14, v195
	s_nop 0
	v_cndmask_b32_e32 v89, v177, v89, vcc
	v_cmp_le_i32_e32 vcc, v197, v189
	v_subrev_u32_e32 v197, 45, v195
	s_nop 0
	v_cndmask_b32_e32 v73, v177, v73, vcc
	v_cmp_le_i32_e32 vcc, v197, v189
	v_add_u32_e32 v197, -13, v195
	s_nop 0
	v_cndmask_b32_e32 v90, v177, v90, vcc
	v_cmp_le_i32_e32 vcc, v197, v189
	v_subrev_u32_e32 v197, 44, v195
	s_nop 0
	v_cndmask_b32_e32 v74, v177, v74, vcc
	v_cmp_le_i32_e32 vcc, v197, v189
	v_add_u32_e32 v197, -12, v195
	s_nop 0
	v_cndmask_b32_e32 v91, v177, v91, vcc
	v_cmp_le_i32_e32 vcc, v197, v189
	v_subrev_u32_e32 v197, 39, v195
	s_nop 0
	v_cndmask_b32_e32 v75, v177, v75, vcc
	v_cmp_le_i32_e32 vcc, v197, v189
	v_add_u32_e32 v197, -7, v195
	s_nop 0
	v_cndmask_b32_e32 v92, v177, v92, vcc
	v_cmp_le_i32_e32 vcc, v197, v189
	v_subrev_u32_e32 v197, 38, v195
	s_nop 0
	v_cndmask_b32_e32 v76, v177, v76, vcc
	v_cmp_le_i32_e32 vcc, v197, v189
	v_add_u32_e32 v197, -6, v195
	s_nop 0
	v_cndmask_b32_e32 v93, v177, v93, vcc
	v_cmp_le_i32_e32 vcc, v197, v189
	v_subrev_u32_e32 v197, 37, v195
	s_nop 0
	v_cndmask_b32_e32 v77, v177, v77, vcc
	v_cmp_le_i32_e32 vcc, v197, v189
	v_add_u32_e32 v197, -5, v195
	s_nop 0
	v_cndmask_b32_e32 v94, v177, v94, vcc
	v_cmp_le_i32_e32 vcc, v197, v189
	v_subrev_u32_e32 v197, 36, v195
	v_add_u32_e32 v195, -4, v195
	v_cndmask_b32_e32 v78, v177, v78, vcc
	v_cmp_le_i32_e32 vcc, v197, v189
	s_nop 1
	v_cndmask_b32_e32 v95, v177, v95, vcc
	v_cmp_le_i32_e32 vcc, v195, v189
	s_nop 1
	v_cndmask_b32_e32 v79, v177, v79, vcc

; #define LAS __attribute__((address_space(3)))
; template <int DQK, int DV, bool CAUSAL, int KT, bool PRIO>
; DI void attn_unit(const bf16_t* Qb, int qpitch, const bf16_t* Kb, int kpitch, const bf16_t* Vtb, int vpitch, bf16_t* Ob, int opitch, int q0, int nt, LAS unsigned char* lds, float kbound, const float* qgain, const int* qpos, float qscale) {
;     ...
;     auto lstore = [&](int buf) {
; #pragma unroll
;         for (int i = 0; i < NKR; ++i) { const int c = tid + i * 512; if (NKC % 512 == 0 || c < NKC) *(LAS u32x4*)(lds + buf * KBUF + (c / KCH) * KS + (c % KCH) * 16) = kreg[i]; }
; #pragma unroll
;         for (int i = 0; i < NVR; ++i) { const int c = tid + i * 512; LAS unsigned char* p = lds + VOFF + buf * VBUF + (c / VCH) * VS + (c % VCH) * 16;
;             *(LAS u32x2*)p = (u32x2){vreg[i].x, vreg[i].y}; *(LAS u32x2*)(p + 8) = (u32x2){vreg[i].z, vreg[i].w}; }
;     };
;     ...
;                     float ps = 0.f;
; #pragma unroll
;                     for (int i = 0; i < 16; ++i) { s0[i] = __builtin_amdgcn_exp2f(s0[i]); ps += s0[i]; asm volatile("" : "+v"(ps)); }
; #pragma unroll
;                     for (int i = 0; i < 16; ++i) { s1[i] = __builtin_amdgcn_exp2f(s1[i]); ps += s1[i]; asm volatile("" : "+v"(ps)); }
;                     lrun += ps;
;                     bf16x8 pf[4];
; #pragma unroll
;                     for (int sf = 0; sf < 2; ++sf) {
;                         u32x4 pw; pw.x = pk2(s0[8 * sf], s0[8 * sf + 1]); pw.y = pk2(s0[8 * sf + 2], s0[8 * sf + 3]); pw.z = pk2(s0[8 * sf + 4], s0[8 * sf + 5]); pw.w = pk2(s0[8 * sf + 6], s0[8 * sf + 7]); pf[sf] = __builtin_bit_cast(bf16x8, pw);
;                         u32x4 pv; pv.x = pk2(s1[8 * sf], s1[8 * sf + 1]); pv.y = pk2(s1[8 * sf + 2], s1[8 * sf + 3]); pv.z = pk2(s1[8 * sf + 4], s1[8 * sf + 5]); pv.w = pk2(s1[8 * sf + 6], s1[8 * sf + 7]); pf[2 + sf] = __builtin_bit_cast(bf16x8, pv);
;                     }
;                     __builtin_amdgcn_sched_barrier(0); __builtin_amdgcn_s_setprio(1); __builtin_amdgcn_sched_barrier(0);
; #pragma unroll
;                     for (int q4 = 0; q4 < 4; ++q4)
; #pragma unroll
;                         for (int d = 0; d < NDB; ++d) o[d] = MFMA32(vf[q4][d], pf[q4], o[d]);
;                     __builtin_amdgcn_sched_barrier(0); __builtin_amdgcn_s_setprio(0); __builtin_amdgcn_sched_barrier(0);
.LBB0_1514:
	s_nop 7
	v_exp_f32_e32 v14, v80
	v_exp_f32_e32 v15, v81
	v_exp_f32_e32 v80, v82
	v_exp_f32_e32 v81, v83
	v_add_f32_e32 v82, 0, v14
	v_exp_f32_e32 v83, v84
	v_add_f32_e32 v82, v15, v82
	v_exp_f32_e32 v84, v85
	v_add_f32_e32 v82, v80, v82
	v_exp_f32_e32 v85, v86
	v_add_f32_e32 v82, v81, v82
	v_exp_f32_e32 v86, v87
	v_add_f32_e32 v82, v83, v82
	v_exp_f32_e32 v87, v88
	v_add_f32_e32 v82, v84, v82
	v_exp_f32_e32 v88, v89
	v_add_f32_e32 v82, v85, v82
	v_exp_f32_e32 v89, v90
	v_add_f32_e32 v82, v86, v82
	v_exp_f32_e32 v90, v91
	v_add_f32_e32 v82, v87, v82
	v_exp_f32_e32 v91, v92
	v_add_f32_e32 v82, v88, v82
	v_exp_f32_e32 v92, v93
	v_add_f32_e32 v82, v89, v82
	v_exp_f32_e32 v93, v94
	v_add_f32_e32 v82, v90, v82
	v_exp_f32_e32 v94, v95
	v_add_f32_e32 v82, v91, v82
	v_exp_f32_e32 v95, v64
	v_add_f32_e32 v82, v92, v82
	v_exp_f32_e32 v194, v66
	v_add_f32_e32 v82, v93, v82
	v_exp_f32_e32 v195, v67
	v_add_f32_e32 v64, v94, v82
	v_exp_f32_e32 v82, v65
	v_exp_f32_e32 v197, v68
	v_add_f32_e32 v64, v95, v64
	v_exp_f32_e32 v198, v69
	v_add_f32_e32 v64, v82, v64
	v_exp_f32_e32 v199, v70
	v_add_f32_e32 v64, v194, v64
	v_exp_f32_e32 v71, v71
	v_add_f32_e32 v64, v195, v64
	v_exp_f32_e32 v200, v72
	v_add_f32_e32 v64, v197, v64
	v_exp_f32_e32 v201, v73
	v_add_f32_e32 v64, v198, v64
	v_exp_f32_e32 v202, v74
	v_add_f32_e32 v64, v199, v64
	v_exp_f32_e32 v203, v75
	v_add_f32_e32 v64, v71, v64
	v_exp_f32_e32 v204, v76
	v_add_f32_e32 v64, v200, v64
	v_exp_f32_e32 v205, v77
	v_add_f32_e32 v64, v201, v64
	v_exp_f32_e32 v206, v78
	v_add_f32_e32 v64, v202, v64
	v_exp_f32_e32 v79, v79
	v_add_f32_e32 v64, v203, v64
	v_cvt_pk_bf16_f32 v65, v80, v81
	v_add_f32_e32 v64, v204, v64
	v_cvt_pk_bf16_f32 v66, v83, v84
	v_add_f32_e32 v64, v205, v64
	v_cvt_pk_bf16_f32 v67, v85, v86
	v_add_f32_e32 v64, v206, v64
	v_cvt_pk_bf16_f32 v68, v95, v82
	v_add_f32_e32 v207, v79, v64
	v_cvt_pk_bf16_f32 v64, v14, v15
	v_cvt_pk_bf16_f32 v69, v194, v195
	v_cvt_pk_bf16_f32 v70, v197, v198
	v_cvt_pk_bf16_f32 v71, v199, v71
	v_cvt_pk_bf16_f32 v72, v87, v88
	v_cvt_pk_bf16_f32 v73, v89, v90
	v_cvt_pk_bf16_f32 v74, v91, v92
	v_cvt_pk_bf16_f32 v75, v93, v94
	v_cvt_pk_bf16_f32 v76, v200, v201
	v_cvt_pk_bf16_f32 v77, v202, v203
	v_cvt_pk_bf16_f32 v78, v204, v205
	v_cvt_pk_bf16_f32 v79, v206, v79
	s_setprio 1
	s_waitcnt lgkmcnt(0)
	s_waitcnt vmcnt(0)
	v_mfma_f32_32x32x16_bf16 v[32:47], v[156:159], v[64:67], v[32:47]
	v_add_f32_e32 v0, v0, v207
	s_xor_b32 s100, s75, 1
	s_mul_i32 s101, s100, 0x6800
	v_add3_u32 v250, s101, v178, v179
	v_mfma_f32_32x32x16_bf16 v[16:31], v[152:155], v[64:67], v[16:31]
	ds_write_b128 v250, v[96:99]
	v_add3_u32 v251, s101, v181, v182
	s_mulk_i32 s100, 0xdc00
	v_mfma_f32_32x32x16_bf16 v[32:47], v[140:143], v[72:75], v[32:47]
	ds_write_b128 v251, v[100:103]
	v_add3_u32 v250, s101, v183, v184
	s_add_i32 s101, s101, s100
	v_mfma_f32_32x32x16_bf16 v[16:31], v[148:151], v[72:75], v[16:31]
	ds_write_b128 v250, v[104:107]
	v_add_u32_e32 v251, s101, v185
	v_add3_u32 v251, v251, v186, s57
	v_mfma_f32_32x32x16_bf16 v[32:47], v[144:147], v[68:71], v[32:47]
	ds_write2_b64 v251, v[108:109], v[110:111] offset1:2
	v_add_u32_e32 v250, s101, v187
	v_add3_u32 v250, v250, v188, s57
	v_mfma_f32_32x32x16_bf16 v[16:31], v[10:13], v[68:71], v[16:31]
	ds_write2_b64 v250, v[112:113], v[114:115] offset1:2
	v_mfma_f32_32x32x16_bf16 v[32:47], v[6:9], v[76:79], v[32:47]
	v_mfma_f32_32x32x16_bf16 v[16:31], v[2:5], v[76:79], v[16:31]
	s_setprio 0
	s_branch .LBB0_1493
	s_nop 0
	s_nop 0
	s_nop 0
	s_nop 0
	s_nop 0
	s_nop 0
	s_nop 0
	s_nop 0
	s_nop 0
	s_nop 0
	s_nop 0
	s_nop 0
	s_nop 0
